# GU/IN K-loops: four 64-bit VALU address adds moved from the DMA-heavy phase-2 load segment to the light phase-3 load segment
# speedup vs baseline: 1.0031x; 1.0031x over previous
; #define PG8_STAGE(bufoff, gbase, voff) do { _Pragma("unroll") for (int _i = 0; _i < 2; ++_i) \
;         __builtin_amdgcn_global_load_lds((const unsigned*)((const char*)(gbase) + (voff)[_i]), (LAS unsigned*)(lds + (bufoff) + ldsw + _i * 8192), 16, 0, 0); } while (0)
; #define PG8_LDA(dst, b, h) do { _Pragma("unroll") for (int m = 0; m < 4; ++m) _Pragma("unroll") for (int k = 0; k < 2; ++k) dst[m][k] = *(const LAS bf16x8*)(lds + PG8_SA(b, h) + aoff + m * 2048 + k * 1024); } while (0)
; #define PG8_MMA(ai, bj, At, Bt) do { __builtin_amdgcn_s_setprio(1); _Pragma("unroll") for (int m = 0; m < 4; ++m) _Pragma("unroll") for (int n = 0; n < 2; ++n) _Pragma("unroll") for (int k = 0; k < 2; ++k) \
;         acc[ai][bj][m][n] = __builtin_amdgcn_mfma_f32_16x16x32_bf16(Bt[n][k], At[m][k], acc[ai][bj][m][n], 0, 0, 0); __builtin_amdgcn_s_setprio(0); } while (0)
; #define PG8_WAIT_V(n) asm volatile("s_waitcnt vmcnt(" #n ")" ::: "memory")
; #define PG8_WAIT_L(n) asm volatile("s_waitcnt lgkmcnt(" #n ")" ::: "memory")
; #define PG8_BAR __builtin_amdgcn_s_barrier()
; #define PG8_SCHED __builtin_amdgcn_sched_barrier(0)
; template <class Epi>
; DI void gemm_phase(LAS unsigned char* lds, const int tid, const Gemm g, const StaticOrder& S, const Epi& E) {
;     ...
;             PG8_WAIT_V(8); PG8_WAIT_L(0); PG8_BAR; PG8_MMA(0, 0, At, B0); PG8_MMA(0, 1, At, B1); PG8_BAR; PG8_SCHED;
;             PG8_LDA(At, 0, 1); PG8_STAGE(PG8_SB(0, 0), b2, voffB); PG8_STAGE(PG8_SB(0, 1), b2 + hstepB, voffB); PG8_STAGE(PG8_SA(0, 0), a2, voffA);
.Lin_wd1:
	s_waitcnt lgkmcnt(0)
	s_barrier
	s_setprio 1
	s_waitcnt lgkmcnt(0)
	v_mfma_f32_16x16x32_bf16 v[126:129], v[140:143], v[180:183], v[126:129]
	v_mfma_f32_16x16x32_bf16 v[122:125], v[156:159], v[180:183], v[122:125]
	v_mfma_f32_16x16x32_bf16 v[118:121], v[140:143], v[188:191], v[118:121]
	v_mfma_f32_16x16x32_bf16 v[110:113], v[156:159], v[188:191], v[110:113]
	v_mfma_f32_16x16x32_bf16 v[102:105], v[140:143], v[196:199], v[102:105]
	v_mfma_f32_16x16x32_bf16 v[94:97], v[156:159], v[196:199], v[94:97]
	v_mfma_f32_16x16x32_bf16 v[86:89], v[140:143], v[208:211], v[86:89]
	v_mfma_f32_16x16x32_bf16 v[78:81], v[156:159], v[208:211], v[78:81]
	v_mfma_f32_16x16x32_bf16 v[126:129], v[152:155], v[184:187], v[126:129]
	v_mfma_f32_16x16x32_bf16 v[122:125], v[160:163], v[184:187], v[122:125]
	v_mfma_f32_16x16x32_bf16 v[118:121], v[152:155], v[192:195], v[118:121]
	v_mfma_f32_16x16x32_bf16 v[110:113], v[160:163], v[192:195], v[110:113]
	v_mfma_f32_16x16x32_bf16 v[102:105], v[152:155], v[200:203], v[102:105]
	v_mfma_f32_16x16x32_bf16 v[94:97], v[160:163], v[200:203], v[94:97]
	v_mfma_f32_16x16x32_bf16 v[86:89], v[152:155], v[212:215], v[86:89]
	v_mfma_f32_16x16x32_bf16 v[78:81], v[160:163], v[212:215], v[78:81]
	s_setprio 0
	s_setprio 1
	v_mfma_f32_16x16x32_bf16 v[114:117], v[164:167], v[180:183], v[114:117]
	v_mfma_f32_16x16x32_bf16 v[106:109], v[172:175], v[180:183], v[106:109]
	v_mfma_f32_16x16x32_bf16 v[98:101], v[164:167], v[188:191], v[98:101]
	v_mfma_f32_16x16x32_bf16 v[90:93], v[172:175], v[188:191], v[90:93]
	v_mfma_f32_16x16x32_bf16 v[82:85], v[164:167], v[196:199], v[82:85]
	v_mfma_f32_16x16x32_bf16 v[74:77], v[172:175], v[196:199], v[74:77]
	v_mfma_f32_16x16x32_bf16 v[70:73], v[164:167], v[208:211], v[70:73]
	v_mfma_f32_16x16x32_bf16 v[66:69], v[172:175], v[208:211], v[66:69]
	v_mfma_f32_16x16x32_bf16 v[114:117], v[168:171], v[184:187], v[114:117]
	v_mfma_f32_16x16x32_bf16 v[106:109], v[176:179], v[184:187], v[106:109]
	v_mfma_f32_16x16x32_bf16 v[98:101], v[168:171], v[192:195], v[98:101]
	v_mfma_f32_16x16x32_bf16 v[90:93], v[176:179], v[192:195], v[90:93]
	v_mfma_f32_16x16x32_bf16 v[82:85], v[168:171], v[200:203], v[82:85]
	v_mfma_f32_16x16x32_bf16 v[74:77], v[176:179], v[200:203], v[74:77]
	v_mfma_f32_16x16x32_bf16 v[70:73], v[168:171], v[212:215], v[70:73]
	v_mfma_f32_16x16x32_bf16 v[66:69], v[176:179], v[212:215], v[66:69]
	s_setprio 0
	s_barrier
	s_add_i32 s26, s83, s30
	s_mov_b32 m0, s26
	ds_read_b128 v[180:183], v150 offset:16384
	ds_read_b128 v[184:187], v150 offset:17408
	ds_read_b128 v[188:191], v150 offset:18432
	ds_read_b128 v[192:195], v150 offset:19456
	ds_read_b128 v[196:199], v150 offset:20480
	ds_read_b128 v[200:203], v150 offset:21504
	ds_read_b128 v[208:211], v150 offset:22528
	ds_read_b128 v[212:215], v150 offset:23552
	global_load_lds_dwordx4 v0, s[60:61]
	s_add_i32 m0, s26, 0x2000
	s_add_u32 s26, s60, 0x40000
	s_addc_u32 s27, s61, 0
	s_add_i32 s83, s84, s30
	global_load_lds_dwordx4 v130, s[60:61]
	s_mov_b32 m0, s83
	global_load_lds_dwordx4 v0, s[26:27]
	s_add_i32 m0, s83, 0x2000
	s_nop 0
	global_load_lds_dwordx4 v130, s[26:27]
	s_mov_b32 m0, s42
	s_nop 0
	global_load_lds_dwordx4 v134, s[62:63]
	s_mov_b32 m0, s43
	s_nop 0
	global_load_lds_dwordx4 v132, s[62:63]
	s_cmp_eq_u32 s100, 0
	s_cbranch_scc1 .Lin_ws2
	s_cmp_eq_u32 s100, 1
	s_cbranch_scc1 .Lin_wr2
	s_waitcnt vmcnt(24)
	s_branch .Lin_wq2

; #define PG8_STAGE(bufoff, gbase, voff) do { _Pragma("unroll") for (int _i = 0; _i < 2; ++_i) \
;         __builtin_amdgcn_global_load_lds((const unsigned*)((const char*)(gbase) + (voff)[_i]), (LAS unsigned*)(lds + (bufoff) + ldsw + _i * 8192), 16, 0, 0); } while (0)
; #define PG8_LDA(dst, b, h) do { _Pragma("unroll") for (int m = 0; m < 4; ++m) _Pragma("unroll") for (int k = 0; k < 2; ++k) dst[m][k] = *(const LAS bf16x8*)(lds + PG8_SA(b, h) + aoff + m * 2048 + k * 1024); } while (0)
; #define PG8_LDB(dst, b, h) do { _Pragma("unroll") for (int n = 0; n < 2; ++n) _Pragma("unroll") for (int k = 0; k < 2; ++k) dst[n][k] = *(const LAS bf16x8*)(lds + PG8_SB(b, h) + boff + n * 2048 + k * 1024); } while (0)
; #define PG8_MMA(ai, bj, At, Bt) do { __builtin_amdgcn_s_setprio(1); _Pragma("unroll") for (int m = 0; m < 4; ++m) _Pragma("unroll") for (int n = 0; n < 2; ++n) _Pragma("unroll") for (int k = 0; k < 2; ++k) \
;         acc[ai][bj][m][n] = __builtin_amdgcn_mfma_f32_16x16x32_bf16(Bt[n][k], At[m][k], acc[ai][bj][m][n], 0, 0, 0); __builtin_amdgcn_s_setprio(0); } while (0)
; #define PG8_WAIT_V(n) asm volatile("s_waitcnt vmcnt(" #n ")" ::: "memory")
; #define PG8_WAIT_L(n) asm volatile("s_waitcnt lgkmcnt(" #n ")" ::: "memory")
; #define PG8_BAR __builtin_amdgcn_s_barrier()
; #define PG8_SCHED __builtin_amdgcn_sched_barrier(0)
; template <class Epi>
; DI void gemm_phase(LAS unsigned char* lds, const int tid, const Gemm g, const StaticOrder& S, const Epi& E) {
;     ...
;             PG8_WAIT_V(8); PG8_WAIT_L(0); PG8_BAR; PG8_MMA(1, 0, At, B0); PG8_MMA(1, 1, At, B1); PG8_BAR; PG8_SCHED;
;             PG8_LDB(B0, 1, 0); PG8_LDB(B1, 1, 1); PG8_SCHED; PG8_LDA(At, 1, 0); PG8_STAGE(PG8_SA(0, 1), a2 + hstepA, voffA);
;             PG8_WAIT_V(8); PG8_WAIT_L(0); PG8_BAR; PG8_MMA(0, 0, At, B0); PG8_MMA(0, 1, At, B1); PG8_BAR; PG8_SCHED;
.Lin_wd2:
	s_waitcnt lgkmcnt(0)
	s_barrier
	s_setprio 1
	s_waitcnt lgkmcnt(0)
	v_mfma_f32_16x16x32_bf16 v[62:65], v[140:143], v[180:183], v[62:65]
	v_mfma_f32_16x16x32_bf16 v[58:61], v[156:159], v[180:183], v[58:61]
	v_mfma_f32_16x16x32_bf16 v[54:57], v[140:143], v[188:191], v[54:57]
	v_mfma_f32_16x16x32_bf16 v[46:49], v[156:159], v[188:191], v[46:49]
	v_mfma_f32_16x16x32_bf16 v[38:41], v[140:143], v[196:199], v[38:41]
	v_mfma_f32_16x16x32_bf16 v[30:33], v[156:159], v[196:199], v[30:33]
	v_mfma_f32_16x16x32_bf16 v[22:25], v[140:143], v[208:211], v[22:25]
	v_mfma_f32_16x16x32_bf16 v[14:17], v[156:159], v[208:211], v[14:17]
	v_mfma_f32_16x16x32_bf16 v[62:65], v[152:155], v[184:187], v[62:65]
	v_mfma_f32_16x16x32_bf16 v[58:61], v[160:163], v[184:187], v[58:61]
	v_mfma_f32_16x16x32_bf16 v[54:57], v[152:155], v[192:195], v[54:57]
	v_mfma_f32_16x16x32_bf16 v[46:49], v[160:163], v[192:195], v[46:49]
	v_mfma_f32_16x16x32_bf16 v[38:41], v[152:155], v[200:203], v[38:41]
	v_mfma_f32_16x16x32_bf16 v[30:33], v[160:163], v[200:203], v[30:33]
	v_mfma_f32_16x16x32_bf16 v[22:25], v[152:155], v[212:215], v[22:25]
	v_mfma_f32_16x16x32_bf16 v[14:17], v[160:163], v[212:215], v[14:17]
	s_setprio 0
	s_setprio 1
	v_mfma_f32_16x16x32_bf16 v[50:53], v[164:167], v[180:183], v[50:53]
	v_mfma_f32_16x16x32_bf16 v[42:45], v[172:175], v[180:183], v[42:45]
	v_mfma_f32_16x16x32_bf16 v[34:37], v[164:167], v[188:191], v[34:37]
	v_mfma_f32_16x16x32_bf16 v[26:29], v[172:175], v[188:191], v[26:29]
	v_mfma_f32_16x16x32_bf16 v[18:21], v[164:167], v[196:199], v[18:21]
	v_mfma_f32_16x16x32_bf16 v[10:13], v[172:175], v[196:199], v[10:13]
	v_mfma_f32_16x16x32_bf16 v[6:9], v[164:167], v[208:211], v[6:9]
	v_mfma_f32_16x16x32_bf16 v[2:5], v[172:175], v[208:211], v[2:5]
	v_mfma_f32_16x16x32_bf16 v[50:53], v[168:171], v[184:187], v[50:53]
	v_mfma_f32_16x16x32_bf16 v[42:45], v[176:179], v[184:187], v[42:45]
	v_mfma_f32_16x16x32_bf16 v[34:37], v[168:171], v[192:195], v[34:37]
	v_mfma_f32_16x16x32_bf16 v[26:29], v[176:179], v[192:195], v[26:29]
	v_mfma_f32_16x16x32_bf16 v[18:21], v[168:171], v[200:203], v[18:21]
	v_mfma_f32_16x16x32_bf16 v[10:13], v[176:179], v[200:203], v[10:13]
	v_mfma_f32_16x16x32_bf16 v[6:9], v[168:171], v[212:215], v[6:9]
	v_mfma_f32_16x16x32_bf16 v[2:5], v[176:179], v[212:215], v[2:5]
	s_setprio 0
	s_barrier
	v_lshl_add_u64 v[204:205], s[60:61], 0, v[0:1]
	v_lshl_add_u64 v[216:217], s[60:61], 0, v[130:131]
	v_lshl_add_u64 v[220:221], s[62:63], 0, v[132:133]
	v_lshl_add_u64 v[218:219], s[62:63], 0, v[134:135]
	s_add_i32 s83, 0, 0x18000
	v_add_u32_e32 v144, s83, v147
	s_add_i32 s84, 0, 0x1c000
	ds_read_b128 v[140:143], v144
	ds_read_b128 v[152:155], v144 offset:1024
	ds_read_b128 v[156:159], v144 offset:2048
	ds_read_b128 v[160:163], v144 offset:3072
	v_add_u32_e32 v144, s84, v147
	ds_read_b128 v[164:167], v144
	ds_read_b128 v[168:171], v144 offset:1024
	ds_read_b128 v[172:175], v144 offset:2048
	ds_read_b128 v[176:179], v144 offset:3072
	s_add_u32 s26, s62, 0x40000
	s_addc_u32 s27, s63, 0
	s_mov_b32 m0, s45
	ds_read_b128 v[180:183], v150 offset:32768
	ds_read_b128 v[184:187], v150 offset:33792
	ds_read_b128 v[188:191], v150 offset:34816
	ds_read_b128 v[192:195], v150 offset:35840
	ds_read_b128 v[196:199], v150 offset:36864
	ds_read_b128 v[200:203], v150 offset:37888
	ds_read_b128 v[208:211], v150 offset:38912
	ds_read_b128 v[212:215], v150 offset:39936
	global_load_lds_dwordx4 v134, s[26:27]
	s_mov_b32 m0, s64
	s_nop 0
	global_load_lds_dwordx4 v132, s[26:27]
	s_waitcnt vmcnt(8)
	s_waitcnt lgkmcnt(0)
	s_barrier
	s_setprio 1
	s_waitcnt lgkmcnt(0)
	v_mfma_f32_16x16x32_bf16 v[126:129], v[140:143], v[180:183], v[126:129]
	v_mfma_f32_16x16x32_bf16 v[122:125], v[156:159], v[180:183], v[122:125]
	v_mfma_f32_16x16x32_bf16 v[118:121], v[140:143], v[188:191], v[118:121]
	v_mfma_f32_16x16x32_bf16 v[110:113], v[156:159], v[188:191], v[110:113]
	v_mfma_f32_16x16x32_bf16 v[102:105], v[140:143], v[196:199], v[102:105]
	v_mfma_f32_16x16x32_bf16 v[94:97], v[156:159], v[196:199], v[94:97]
	v_mfma_f32_16x16x32_bf16 v[86:89], v[140:143], v[208:211], v[86:89]
	v_mfma_f32_16x16x32_bf16 v[78:81], v[156:159], v[208:211], v[78:81]
	v_mfma_f32_16x16x32_bf16 v[126:129], v[152:155], v[184:187], v[126:129]
	v_mfma_f32_16x16x32_bf16 v[122:125], v[160:163], v[184:187], v[122:125]
	v_mfma_f32_16x16x32_bf16 v[118:121], v[152:155], v[192:195], v[118:121]
	v_mfma_f32_16x16x32_bf16 v[110:113], v[160:163], v[192:195], v[110:113]
	v_mfma_f32_16x16x32_bf16 v[102:105], v[152:155], v[200:203], v[102:105]
	v_mfma_f32_16x16x32_bf16 v[94:97], v[160:163], v[200:203], v[94:97]
	v_mfma_f32_16x16x32_bf16 v[86:89], v[152:155], v[212:215], v[86:89]
	v_mfma_f32_16x16x32_bf16 v[78:81], v[160:163], v[212:215], v[78:81]
	s_setprio 0
	s_setprio 1
	v_mfma_f32_16x16x32_bf16 v[114:117], v[164:167], v[180:183], v[114:117]
	v_mfma_f32_16x16x32_bf16 v[106:109], v[172:175], v[180:183], v[106:109]
	v_mfma_f32_16x16x32_bf16 v[98:101], v[164:167], v[188:191], v[98:101]
	v_mfma_f32_16x16x32_bf16 v[90:93], v[172:175], v[188:191], v[90:93]
	v_mfma_f32_16x16x32_bf16 v[82:85], v[164:167], v[196:199], v[82:85]
	v_mfma_f32_16x16x32_bf16 v[74:77], v[172:175], v[196:199], v[74:77]
	v_mfma_f32_16x16x32_bf16 v[70:73], v[164:167], v[208:211], v[70:73]
	v_mfma_f32_16x16x32_bf16 v[66:69], v[172:175], v[208:211], v[66:69]
	v_mfma_f32_16x16x32_bf16 v[114:117], v[168:171], v[184:187], v[114:117]
	v_mfma_f32_16x16x32_bf16 v[106:109], v[176:179], v[184:187], v[106:109]
	v_mfma_f32_16x16x32_bf16 v[98:101], v[168:171], v[192:195], v[98:101]
	v_mfma_f32_16x16x32_bf16 v[90:93], v[176:179], v[192:195], v[90:93]
	v_mfma_f32_16x16x32_bf16 v[82:85], v[168:171], v[200:203], v[82:85]
	v_mfma_f32_16x16x32_bf16 v[74:77], v[176:179], v[200:203], v[74:77]
	v_mfma_f32_16x16x32_bf16 v[70:73], v[168:171], v[212:215], v[70:73]
	v_mfma_f32_16x16x32_bf16 v[66:69], v[176:179], v[212:215], v[66:69]
	s_setprio 0
	s_barrier
; #define PG8_STAGE(bufoff, gbase, voff) do { _Pragma("unroll") for (int _i = 0; _i < 2; ++_i) \
;         __builtin_amdgcn_global_load_lds((const unsigned*)((const char*)(gbase) + (voff)[_i]), (LAS unsigned*)(lds + (bufoff) + ldsw + _i * 8192), 16, 0, 0); } while (0)
; #define PG8_LDA(dst, b, h) do { _Pragma("unroll") for (int m = 0; m < 4; ++m) _Pragma("unroll") for (int k = 0; k < 2; ++k) dst[m][k] = *(const LAS bf16x8*)(lds + PG8_SA(b, h) + aoff + m * 2048 + k * 1024); } while (0)
; #define PG8_MMA(ai, bj, At, Bt) do { __builtin_amdgcn_s_setprio(1); _Pragma("unroll") for (int m = 0; m < 4; ++m) _Pragma("unroll") for (int n = 0; n < 2; ++n) _Pragma("unroll") for (int k = 0; k < 2; ++k) \
;         acc[ai][bj][m][n] = __builtin_amdgcn_mfma_f32_16x16x32_bf16(Bt[n][k], At[m][k], acc[ai][bj][m][n], 0, 0, 0); __builtin_amdgcn_s_setprio(0); } while (0)
; #define PG8_WAIT_V(n) asm volatile("s_waitcnt vmcnt(" #n ")" ::: "memory")
; #define PG8_WAIT_L(n) asm volatile("s_waitcnt lgkmcnt(" #n ")" ::: "memory")
; #define PG8_BAR __builtin_amdgcn_s_barrier()
; #define PG8_SCHED __builtin_amdgcn_sched_barrier(0)
; template <class Epi>
; DI void gemm_phase(LAS unsigned char* lds, const int tid, const Gemm g, const StaticOrder& S, const Epi& E) {
;     ...
;             PG8_LDA(At, 1, 1); PG8_STAGE(PG8_SB(1, 0), b3, voffB); PG8_STAGE(PG8_SB(1, 1), b3 + hstepB, voffB); PG8_STAGE(PG8_SA(1, 0), a3, voffA);
;             PG8_WAIT_V(8); PG8_WAIT_L(0); PG8_BAR; PG8_MMA(1, 0, At, B0); PG8_MMA(1, 1, At, B1); PG8_BAR; PG8_SCHED;
;         }
;         if (wr == 0) PG8_BAR;
	s_add_i32 s26, s83, s30
	v_lshl_add_u64 v[204:205], v[204:205], 0, s[54:55]
	s_mov_b32 m0, s26
	ds_read_b128 v[180:183], v150 offset:49152
	ds_read_b128 v[184:187], v150 offset:50176
	ds_read_b128 v[188:191], v150 offset:51200
	ds_read_b128 v[192:195], v150 offset:52224
	ds_read_b128 v[196:199], v150 offset:53248
	ds_read_b128 v[200:203], v150 offset:54272
	ds_read_b128 v[208:211], v150 offset:55296
	ds_read_b128 v[212:215], v150 offset:56320
	global_load_lds_dwordx4 v[204:205], off
	s_add_i32 m0, s26, 0x2000
	s_add_u32 s26, s60, 0x40080
	v_lshl_add_u64 v[204:205], v[216:217], 0, s[54:55]
	s_addc_u32 s27, s61, 0
	s_add_i32 s60, s84, s30
	global_load_lds_dwordx4 v[204:205], off
	s_mov_b32 m0, s60
	s_nop 0
	global_load_lds_dwordx4 v0, s[26:27]
	s_add_i32 m0, s60, 0x2000
	s_nop 0
	global_load_lds_dwordx4 v130, s[26:27]
	v_lshl_add_u64 v[204:205], v[218:219], 0, s[54:55]
	s_mov_b32 m0, s66
	s_nop 0
	global_load_lds_dwordx4 v[204:205], off
	v_lshl_add_u64 v[204:205], v[220:221], 0, s[54:55]
	s_mov_b32 m0, s67
	s_nop 0
	global_load_lds_dwordx4 v[204:205], off
	s_waitcnt vmcnt(8)
	s_waitcnt lgkmcnt(0)
	s_barrier
	s_setprio 1
	s_waitcnt lgkmcnt(0)
	v_mfma_f32_16x16x32_bf16 v[62:65], v[140:143], v[180:183], v[62:65]
	v_mfma_f32_16x16x32_bf16 v[58:61], v[156:159], v[180:183], v[58:61]
	v_mfma_f32_16x16x32_bf16 v[54:57], v[140:143], v[188:191], v[54:57]
	v_mfma_f32_16x16x32_bf16 v[46:49], v[156:159], v[188:191], v[46:49]
	v_mfma_f32_16x16x32_bf16 v[38:41], v[140:143], v[196:199], v[38:41]
	v_mfma_f32_16x16x32_bf16 v[30:33], v[156:159], v[196:199], v[30:33]
	v_mfma_f32_16x16x32_bf16 v[22:25], v[140:143], v[208:211], v[22:25]
	v_mfma_f32_16x16x32_bf16 v[14:17], v[156:159], v[208:211], v[14:17]
	v_mfma_f32_16x16x32_bf16 v[62:65], v[152:155], v[184:187], v[62:65]
	v_mfma_f32_16x16x32_bf16 v[58:61], v[160:163], v[184:187], v[58:61]
	v_mfma_f32_16x16x32_bf16 v[54:57], v[152:155], v[192:195], v[54:57]
	v_mfma_f32_16x16x32_bf16 v[46:49], v[160:163], v[192:195], v[46:49]
	v_mfma_f32_16x16x32_bf16 v[38:41], v[152:155], v[200:203], v[38:41]
	v_mfma_f32_16x16x32_bf16 v[30:33], v[160:163], v[200:203], v[30:33]
	v_mfma_f32_16x16x32_bf16 v[22:25], v[152:155], v[212:215], v[22:25]
	v_mfma_f32_16x16x32_bf16 v[14:17], v[160:163], v[212:215], v[14:17]
	s_setprio 0
	s_setprio 1
	v_mfma_f32_16x16x32_bf16 v[50:53], v[164:167], v[180:183], v[50:53]
	v_mfma_f32_16x16x32_bf16 v[42:45], v[172:175], v[180:183], v[42:45]
	v_mfma_f32_16x16x32_bf16 v[34:37], v[164:167], v[188:191], v[34:37]
	v_mfma_f32_16x16x32_bf16 v[26:29], v[172:175], v[188:191], v[26:29]
	v_mfma_f32_16x16x32_bf16 v[18:21], v[164:167], v[196:199], v[18:21]
	v_mfma_f32_16x16x32_bf16 v[10:13], v[172:175], v[196:199], v[10:13]
	v_mfma_f32_16x16x32_bf16 v[6:9], v[164:167], v[208:211], v[6:9]
	v_mfma_f32_16x16x32_bf16 v[2:5], v[172:175], v[208:211], v[2:5]
	v_mfma_f32_16x16x32_bf16 v[50:53], v[168:171], v[184:187], v[50:53]
	v_mfma_f32_16x16x32_bf16 v[42:45], v[176:179], v[184:187], v[42:45]
	v_mfma_f32_16x16x32_bf16 v[34:37], v[168:171], v[192:195], v[34:37]
	v_mfma_f32_16x16x32_bf16 v[26:29], v[176:179], v[192:195], v[26:29]
	v_mfma_f32_16x16x32_bf16 v[18:21], v[168:171], v[200:203], v[18:21]
	v_mfma_f32_16x16x32_bf16 v[10:13], v[176:179], v[200:203], v[10:13]
	v_mfma_f32_16x16x32_bf16 v[6:9], v[168:171], v[212:215], v[6:9]
	v_mfma_f32_16x16x32_bf16 v[2:5], v[176:179], v[212:215], v[2:5]
	s_setprio 0
	s_barrier
	s_add_i32 s82, s82, 2
	s_add_u32 s58, s58, 0x100
	s_addc_u32 s59, s59, 0
	s_add_u32 s80, s80, 0x100
	s_addc_u32 s81, s81, 0
	s_cmp_gt_u32 s82, 13
	s_cbranch_scc0 .LBB0_420
	s_and_b64 vcc, exec, s[10:11]
	s_cbranch_vccz .LBB0_423
	s_barrier

; #define PG8_STAGE(bufoff, gbase, voff) do { _Pragma("unroll") for (int _i = 0; _i < 2; ++_i) \
;         __builtin_amdgcn_global_load_lds((const unsigned*)((const char*)(gbase) + (voff)[_i]), (LAS unsigned*)(lds + (bufoff) + ldsw + _i * 8192), 16, 0, 0); } while (0)
; #define PG8_LDA(dst, b, h) do { _Pragma("unroll") for (int m = 0; m < 4; ++m) _Pragma("unroll") for (int k = 0; k < 2; ++k) dst[m][k] = *(const LAS bf16x8*)(lds + PG8_SA(b, h) + aoff + m * 2048 + k * 1024); } while (0)
; #define PG8_MMA(ai, bj, At, Bt) do { __builtin_amdgcn_s_setprio(1); _Pragma("unroll") for (int m = 0; m < 4; ++m) _Pragma("unroll") for (int n = 0; n < 2; ++n) _Pragma("unroll") for (int k = 0; k < 2; ++k) \
;         acc[ai][bj][m][n] = __builtin_amdgcn_mfma_f32_16x16x32_bf16(Bt[n][k], At[m][k], acc[ai][bj][m][n], 0, 0, 0); __builtin_amdgcn_s_setprio(0); } while (0)
; #define PG8_WAIT_V(n) asm volatile("s_waitcnt vmcnt(" #n ")" ::: "memory")
; #define PG8_WAIT_L(n) asm volatile("s_waitcnt lgkmcnt(" #n ")" ::: "memory")
; #define PG8_BAR __builtin_amdgcn_s_barrier()
; #define PG8_SCHED __builtin_amdgcn_sched_barrier(0)
; template <class Epi>
; DI void gemm_phase(LAS unsigned char* lds, const int tid, const Gemm g, const StaticOrder& S, const Epi& E) {
;     ...
;             PG8_WAIT_V(8); PG8_WAIT_L(0); PG8_BAR; PG8_MMA(0, 0, At, B0); PG8_MMA(0, 1, At, B1); PG8_BAR; PG8_SCHED;
;             PG8_LDA(At, 0, 1); PG8_STAGE(PG8_SB(0, 0), b2, voffB); PG8_STAGE(PG8_SB(0, 1), b2 + hstepB, voffB); PG8_STAGE(PG8_SA(0, 0), a2, voffA);
.Lgu_wd1:
	s_waitcnt lgkmcnt(0)
	s_barrier
	s_setprio 1
	s_waitcnt lgkmcnt(0)
	v_mfma_f32_16x16x32_bf16 v[126:129], v[156:159], v[188:191], v[126:129]
	v_mfma_f32_16x16x32_bf16 v[118:121], v[164:167], v[188:191], v[118:121]
	v_mfma_f32_16x16x32_bf16 v[110:113], v[156:159], v[196:199], v[110:113]
	v_mfma_f32_16x16x32_bf16 v[102:105], v[164:167], v[196:199], v[102:105]
	v_mfma_f32_16x16x32_bf16 v[94:97], v[156:159], v[212:215], v[94:97]
	v_mfma_f32_16x16x32_bf16 v[86:89], v[164:167], v[212:215], v[86:89]
	v_mfma_f32_16x16x32_bf16 v[78:81], v[156:159], v[220:223], v[78:81]
	v_mfma_f32_16x16x32_bf16 v[70:73], v[164:167], v[220:223], v[70:73]
	v_mfma_f32_16x16x32_bf16 v[126:129], v[160:163], v[192:195], v[126:129]
	v_mfma_f32_16x16x32_bf16 v[118:121], v[168:171], v[192:195], v[118:121]
	v_mfma_f32_16x16x32_bf16 v[110:113], v[160:163], v[208:211], v[110:113]
	v_mfma_f32_16x16x32_bf16 v[102:105], v[168:171], v[208:211], v[102:105]
	v_mfma_f32_16x16x32_bf16 v[94:97], v[160:163], v[216:219], v[94:97]
	v_mfma_f32_16x16x32_bf16 v[86:89], v[168:171], v[216:219], v[86:89]
	v_mfma_f32_16x16x32_bf16 v[78:81], v[160:163], v[224:227], v[78:81]
	v_mfma_f32_16x16x32_bf16 v[70:73], v[168:171], v[224:227], v[70:73]
	s_setprio 0
	s_setprio 1
	v_mfma_f32_16x16x32_bf16 v[122:125], v[172:175], v[188:191], v[122:125]
	v_mfma_f32_16x16x32_bf16 v[114:117], v[180:183], v[188:191], v[114:117]
	v_mfma_f32_16x16x32_bf16 v[106:109], v[172:175], v[196:199], v[106:109]
	v_mfma_f32_16x16x32_bf16 v[98:101], v[180:183], v[196:199], v[98:101]
	v_mfma_f32_16x16x32_bf16 v[90:93], v[172:175], v[212:215], v[90:93]
	v_mfma_f32_16x16x32_bf16 v[82:85], v[180:183], v[212:215], v[82:85]
	v_mfma_f32_16x16x32_bf16 v[74:77], v[172:175], v[220:223], v[74:77]
	v_mfma_f32_16x16x32_bf16 v[66:69], v[180:183], v[220:223], v[66:69]
	v_mfma_f32_16x16x32_bf16 v[122:125], v[176:179], v[192:195], v[122:125]
	v_mfma_f32_16x16x32_bf16 v[114:117], v[184:187], v[192:195], v[114:117]
	v_mfma_f32_16x16x32_bf16 v[106:109], v[176:179], v[208:211], v[106:109]
	v_mfma_f32_16x16x32_bf16 v[98:101], v[184:187], v[208:211], v[98:101]
	v_mfma_f32_16x16x32_bf16 v[90:93], v[176:179], v[216:219], v[90:93]
	v_mfma_f32_16x16x32_bf16 v[82:85], v[184:187], v[216:219], v[82:85]
	v_mfma_f32_16x16x32_bf16 v[74:77], v[176:179], v[224:227], v[74:77]
	v_mfma_f32_16x16x32_bf16 v[66:69], v[184:187], v[224:227], v[66:69]
	s_setprio 0
	s_barrier
	s_add_i32 s59, s59, s25
	s_mov_b32 m0, s59
	ds_read_b128 v[188:191], v155 offset:16384
	ds_read_b128 v[192:195], v155 offset:17408
	ds_read_b128 v[196:199], v155 offset:18432
	ds_read_b128 v[208:211], v155 offset:19456
	ds_read_b128 v[212:215], v155 offset:20480
	ds_read_b128 v[216:219], v155 offset:21504
	ds_read_b128 v[220:223], v155 offset:22528
	ds_read_b128 v[224:227], v155 offset:23552
	global_load_lds_dwordx4 v0, s[36:37]
	s_add_i32 m0, s59, 0x2000
	s_add_u32 s60, s36, 0x40000
	s_addc_u32 s61, s37, 0
	s_add_i32 s59, s62, s25
	global_load_lds_dwordx4 v130, s[36:37]
	s_mov_b32 m0, s59
	global_load_lds_dwordx4 v0, s[60:61]
	s_add_i32 m0, s59, 0x2000
	s_nop 0
	global_load_lds_dwordx4 v130, s[60:61]
	s_mov_b32 m0, s30
	s_nop 0
	global_load_lds_dwordx4 v134, s[40:41]
	s_mov_b32 m0, s31
	s_nop 0
	global_load_lds_dwordx4 v132, s[40:41]
	s_cmp_eq_u32 s100, 0
	s_cbranch_scc1 .Lgu_ws2
	s_cmp_eq_u32 s100, 1
	s_cbranch_scc1 .Lgu_wr2
	s_waitcnt vmcnt(16)
	s_branch .Lgu_wq2

; #define PG8_STAGE(bufoff, gbase, voff) do { _Pragma("unroll") for (int _i = 0; _i < 2; ++_i) \
;         __builtin_amdgcn_global_load_lds((const unsigned*)((const char*)(gbase) + (voff)[_i]), (LAS unsigned*)(lds + (bufoff) + ldsw + _i * 8192), 16, 0, 0); } while (0)
; #define PG8_LDA(dst, b, h) do { _Pragma("unroll") for (int m = 0; m < 4; ++m) _Pragma("unroll") for (int k = 0; k < 2; ++k) dst[m][k] = *(const LAS bf16x8*)(lds + PG8_SA(b, h) + aoff + m * 2048 + k * 1024); } while (0)
; #define PG8_LDB(dst, b, h) do { _Pragma("unroll") for (int n = 0; n < 2; ++n) _Pragma("unroll") for (int k = 0; k < 2; ++k) dst[n][k] = *(const LAS bf16x8*)(lds + PG8_SB(b, h) + boff + n * 2048 + k * 1024); } while (0)
; #define PG8_MMA(ai, bj, At, Bt) do { __builtin_amdgcn_s_setprio(1); _Pragma("unroll") for (int m = 0; m < 4; ++m) _Pragma("unroll") for (int n = 0; n < 2; ++n) _Pragma("unroll") for (int k = 0; k < 2; ++k) \
;         acc[ai][bj][m][n] = __builtin_amdgcn_mfma_f32_16x16x32_bf16(Bt[n][k], At[m][k], acc[ai][bj][m][n], 0, 0, 0); __builtin_amdgcn_s_setprio(0); } while (0)
; #define PG8_WAIT_V(n) asm volatile("s_waitcnt vmcnt(" #n ")" ::: "memory")
; #define PG8_WAIT_L(n) asm volatile("s_waitcnt lgkmcnt(" #n ")" ::: "memory")
; #define PG8_BAR __builtin_amdgcn_s_barrier()
; #define PG8_SCHED __builtin_amdgcn_sched_barrier(0)
; template <class Epi>
; DI void gemm_phase(LAS unsigned char* lds, const int tid, const Gemm g, const StaticOrder& S, const Epi& E) {
;     ...
;             PG8_WAIT_V(8); PG8_WAIT_L(0); PG8_BAR; PG8_MMA(1, 0, At, B0); PG8_MMA(1, 1, At, B1); PG8_BAR; PG8_SCHED;
;             PG8_LDB(B0, 1, 0); PG8_LDB(B1, 1, 1); PG8_SCHED; PG8_LDA(At, 1, 0); PG8_STAGE(PG8_SA(0, 1), a2 + hstepA, voffA);
;             PG8_WAIT_V(8); PG8_WAIT_L(0); PG8_BAR; PG8_MMA(0, 0, At, B0); PG8_MMA(0, 1, At, B1); PG8_BAR; PG8_SCHED;
.Lgu_wd2:
	s_waitcnt lgkmcnt(0)
	s_barrier
	s_setprio 1
	s_waitcnt lgkmcnt(0)
	v_mfma_f32_16x16x32_bf16 v[62:65], v[156:159], v[188:191], v[62:65]
	v_mfma_f32_16x16x32_bf16 v[54:57], v[164:167], v[188:191], v[54:57]
	v_mfma_f32_16x16x32_bf16 v[46:49], v[156:159], v[196:199], v[46:49]
	v_mfma_f32_16x16x32_bf16 v[38:41], v[164:167], v[196:199], v[38:41]
	v_mfma_f32_16x16x32_bf16 v[30:33], v[156:159], v[212:215], v[30:33]
	v_mfma_f32_16x16x32_bf16 v[22:25], v[164:167], v[212:215], v[22:25]
	v_mfma_f32_16x16x32_bf16 v[14:17], v[156:159], v[220:223], v[14:17]
	v_mfma_f32_16x16x32_bf16 v[6:9], v[164:167], v[220:223], v[6:9]
	v_mfma_f32_16x16x32_bf16 v[62:65], v[160:163], v[192:195], v[62:65]
	v_mfma_f32_16x16x32_bf16 v[54:57], v[168:171], v[192:195], v[54:57]
	v_mfma_f32_16x16x32_bf16 v[46:49], v[160:163], v[208:211], v[46:49]
	v_mfma_f32_16x16x32_bf16 v[38:41], v[168:171], v[208:211], v[38:41]
	v_mfma_f32_16x16x32_bf16 v[30:33], v[160:163], v[216:219], v[30:33]
	v_mfma_f32_16x16x32_bf16 v[22:25], v[168:171], v[216:219], v[22:25]
	v_mfma_f32_16x16x32_bf16 v[14:17], v[160:163], v[224:227], v[14:17]
	v_mfma_f32_16x16x32_bf16 v[6:9], v[168:171], v[224:227], v[6:9]
	s_setprio 0
	s_setprio 1
	v_mfma_f32_16x16x32_bf16 v[58:61], v[172:175], v[188:191], v[58:61]
	v_mfma_f32_16x16x32_bf16 v[50:53], v[180:183], v[188:191], v[50:53]
	v_mfma_f32_16x16x32_bf16 v[42:45], v[172:175], v[196:199], v[42:45]
	v_mfma_f32_16x16x32_bf16 v[34:37], v[180:183], v[196:199], v[34:37]
	v_mfma_f32_16x16x32_bf16 v[26:29], v[172:175], v[212:215], v[26:29]
	v_mfma_f32_16x16x32_bf16 v[18:21], v[180:183], v[212:215], v[18:21]
	v_mfma_f32_16x16x32_bf16 v[10:13], v[172:175], v[220:223], v[10:13]
	v_mfma_f32_16x16x32_bf16 v[2:5], v[180:183], v[220:223], v[2:5]
	v_mfma_f32_16x16x32_bf16 v[58:61], v[176:179], v[192:195], v[58:61]
	v_mfma_f32_16x16x32_bf16 v[50:53], v[184:187], v[192:195], v[50:53]
	v_mfma_f32_16x16x32_bf16 v[42:45], v[176:179], v[208:211], v[42:45]
	v_mfma_f32_16x16x32_bf16 v[34:37], v[184:187], v[208:211], v[34:37]
	v_mfma_f32_16x16x32_bf16 v[26:29], v[176:179], v[216:219], v[26:29]
	v_mfma_f32_16x16x32_bf16 v[18:21], v[184:187], v[216:219], v[18:21]
	v_mfma_f32_16x16x32_bf16 v[10:13], v[176:179], v[224:227], v[10:13]
	v_mfma_f32_16x16x32_bf16 v[2:5], v[184:187], v[224:227], v[2:5]
	s_setprio 0
	s_barrier
	v_lshl_add_u64 v[140:141], s[36:37], 0, v[0:1]
	v_lshl_add_u64 v[148:149], s[36:37], 0, v[130:131]
	v_lshl_add_u64 v[202:203], s[40:41], 0, v[132:133]
	v_lshl_add_u64 v[200:201], s[40:41], 0, v[134:135]
	s_add_i32 s59, 0, 0x18000
	v_add_u32_e32 v142, s59, v147
	s_add_i32 s60, 0, 0x1c000
	ds_read_b128 v[156:159], v142
	ds_read_b128 v[160:163], v142 offset:1024
	ds_read_b128 v[164:167], v142 offset:2048
	ds_read_b128 v[168:171], v142 offset:3072
	v_add_u32_e32 v142, s60, v147
	ds_read_b128 v[172:175], v142
	ds_read_b128 v[176:179], v142 offset:1024
	ds_read_b128 v[180:183], v142 offset:2048
	ds_read_b128 v[184:187], v142 offset:3072
	s_add_u32 s40, s40, 0x40000
	s_addc_u32 s41, s41, 0
	s_mov_b32 m0, s38
	ds_read_b128 v[188:191], v155 offset:32768
	ds_read_b128 v[192:195], v155 offset:33792
	ds_read_b128 v[196:199], v155 offset:34816
	ds_read_b128 v[208:211], v155 offset:35840
	ds_read_b128 v[212:215], v155 offset:36864
	ds_read_b128 v[216:219], v155 offset:37888
	ds_read_b128 v[220:223], v155 offset:38912
	ds_read_b128 v[224:227], v155 offset:39936
	global_load_lds_dwordx4 v134, s[40:41]
	s_mov_b32 m0, s39
	s_nop 0
	global_load_lds_dwordx4 v132, s[40:41]
	s_waitcnt vmcnt(8)
	s_waitcnt lgkmcnt(0)
	s_barrier
	s_setprio 1
	s_waitcnt lgkmcnt(0)
	v_mfma_f32_16x16x32_bf16 v[126:129], v[156:159], v[188:191], v[126:129]
	v_mfma_f32_16x16x32_bf16 v[118:121], v[164:167], v[188:191], v[118:121]
	v_mfma_f32_16x16x32_bf16 v[110:113], v[156:159], v[196:199], v[110:113]
	v_mfma_f32_16x16x32_bf16 v[102:105], v[164:167], v[196:199], v[102:105]
	v_mfma_f32_16x16x32_bf16 v[94:97], v[156:159], v[212:215], v[94:97]
	v_mfma_f32_16x16x32_bf16 v[86:89], v[164:167], v[212:215], v[86:89]
	v_mfma_f32_16x16x32_bf16 v[78:81], v[156:159], v[220:223], v[78:81]
	v_mfma_f32_16x16x32_bf16 v[70:73], v[164:167], v[220:223], v[70:73]
	v_mfma_f32_16x16x32_bf16 v[126:129], v[160:163], v[192:195], v[126:129]
	v_mfma_f32_16x16x32_bf16 v[118:121], v[168:171], v[192:195], v[118:121]
	v_mfma_f32_16x16x32_bf16 v[110:113], v[160:163], v[208:211], v[110:113]
	v_mfma_f32_16x16x32_bf16 v[102:105], v[168:171], v[208:211], v[102:105]
	v_mfma_f32_16x16x32_bf16 v[94:97], v[160:163], v[216:219], v[94:97]
	v_mfma_f32_16x16x32_bf16 v[86:89], v[168:171], v[216:219], v[86:89]
	v_mfma_f32_16x16x32_bf16 v[78:81], v[160:163], v[224:227], v[78:81]
	v_mfma_f32_16x16x32_bf16 v[70:73], v[168:171], v[224:227], v[70:73]
	s_setprio 0
	s_setprio 1
	v_mfma_f32_16x16x32_bf16 v[122:125], v[172:175], v[188:191], v[122:125]
	v_mfma_f32_16x16x32_bf16 v[114:117], v[180:183], v[188:191], v[114:117]
	v_mfma_f32_16x16x32_bf16 v[106:109], v[172:175], v[196:199], v[106:109]
	v_mfma_f32_16x16x32_bf16 v[98:101], v[180:183], v[196:199], v[98:101]
	v_mfma_f32_16x16x32_bf16 v[90:93], v[172:175], v[212:215], v[90:93]
	v_mfma_f32_16x16x32_bf16 v[82:85], v[180:183], v[212:215], v[82:85]
	v_mfma_f32_16x16x32_bf16 v[74:77], v[172:175], v[220:223], v[74:77]
	v_mfma_f32_16x16x32_bf16 v[66:69], v[180:183], v[220:223], v[66:69]
	v_mfma_f32_16x16x32_bf16 v[122:125], v[176:179], v[192:195], v[122:125]
	v_mfma_f32_16x16x32_bf16 v[114:117], v[184:187], v[192:195], v[114:117]
	v_mfma_f32_16x16x32_bf16 v[106:109], v[176:179], v[208:211], v[106:109]
	v_mfma_f32_16x16x32_bf16 v[98:101], v[184:187], v[208:211], v[98:101]
	v_mfma_f32_16x16x32_bf16 v[90:93], v[176:179], v[216:219], v[90:93]
	v_mfma_f32_16x16x32_bf16 v[82:85], v[184:187], v[216:219], v[82:85]
	v_mfma_f32_16x16x32_bf16 v[74:77], v[176:179], v[224:227], v[74:77]
	v_mfma_f32_16x16x32_bf16 v[66:69], v[184:187], v[224:227], v[66:69]
	s_setprio 0
	s_barrier
; #define PG8_STAGE(bufoff, gbase, voff) do { _Pragma("unroll") for (int _i = 0; _i < 2; ++_i) \
;         __builtin_amdgcn_global_load_lds((const unsigned*)((const char*)(gbase) + (voff)[_i]), (LAS unsigned*)(lds + (bufoff) + ldsw + _i * 8192), 16, 0, 0); } while (0)
; #define PG8_LDA(dst, b, h) do { _Pragma("unroll") for (int m = 0; m < 4; ++m) _Pragma("unroll") for (int k = 0; k < 2; ++k) dst[m][k] = *(const LAS bf16x8*)(lds + PG8_SA(b, h) + aoff + m * 2048 + k * 1024); } while (0)
; #define PG8_MMA(ai, bj, At, Bt) do { __builtin_amdgcn_s_setprio(1); _Pragma("unroll") for (int m = 0; m < 4; ++m) _Pragma("unroll") for (int n = 0; n < 2; ++n) _Pragma("unroll") for (int k = 0; k < 2; ++k) \
;         acc[ai][bj][m][n] = __builtin_amdgcn_mfma_f32_16x16x32_bf16(Bt[n][k], At[m][k], acc[ai][bj][m][n], 0, 0, 0); __builtin_amdgcn_s_setprio(0); } while (0)
; #define PG8_WAIT_V(n) asm volatile("s_waitcnt vmcnt(" #n ")" ::: "memory")
; #define PG8_WAIT_L(n) asm volatile("s_waitcnt lgkmcnt(" #n ")" ::: "memory")
; #define PG8_BAR __builtin_amdgcn_s_barrier()
; #define PG8_SCHED __builtin_amdgcn_sched_barrier(0)
; template <class Epi>
; DI void gemm_phase(LAS unsigned char* lds, const int tid, const Gemm g, const StaticOrder& S, const Epi& E) {
;     ...
;             PG8_LDA(At, 1, 1); PG8_STAGE(PG8_SB(1, 0), b3, voffB); PG8_STAGE(PG8_SB(1, 1), b3 + hstepB, voffB); PG8_STAGE(PG8_SA(1, 0), a3, voffA);
;             PG8_WAIT_V(8); PG8_WAIT_L(0); PG8_BAR; PG8_MMA(1, 0, At, B0); PG8_MMA(1, 1, At, B1); PG8_BAR; PG8_SCHED;
;         }
;         if (wr == 0) PG8_BAR;
	s_add_i32 s40, s59, s25
	v_lshl_add_u64 v[140:141], v[140:141], 0, s[54:55]
	s_mov_b32 m0, s40
	ds_read_b128 v[188:191], v155 offset:49152
	ds_read_b128 v[192:195], v155 offset:50176
	ds_read_b128 v[196:199], v155 offset:51200
	ds_read_b128 v[208:211], v155 offset:52224
	ds_read_b128 v[212:215], v155 offset:53248
	ds_read_b128 v[216:219], v155 offset:54272
	ds_read_b128 v[220:223], v155 offset:55296
	ds_read_b128 v[224:227], v155 offset:56320
	global_load_lds_dwordx4 v[140:141], off
	s_add_i32 m0, s40, 0x2000
	s_add_u32 s36, s36, 0x40080
	v_lshl_add_u64 v[140:141], v[148:149], 0, s[54:55]
	s_addc_u32 s37, s37, 0
	s_add_i32 s40, s60, s25
	global_load_lds_dwordx4 v[140:141], off
	s_mov_b32 m0, s40
	s_nop 0
	global_load_lds_dwordx4 v0, s[36:37]
	s_add_i32 m0, s40, 0x2000
	s_nop 0
	global_load_lds_dwordx4 v130, s[36:37]
	v_lshl_add_u64 v[140:141], v[200:201], 0, s[54:55]
	s_mov_b32 m0, s42
	s_nop 0
	global_load_lds_dwordx4 v[140:141], off
	v_lshl_add_u64 v[140:141], v[202:203], 0, s[54:55]
	s_mov_b32 m0, s43
	s_nop 0
	global_load_lds_dwordx4 v[140:141], off
	s_waitcnt vmcnt(8)
	s_waitcnt lgkmcnt(0)
	s_barrier
	s_setprio 1
	s_waitcnt lgkmcnt(0)
	v_mfma_f32_16x16x32_bf16 v[62:65], v[156:159], v[188:191], v[62:65]
	v_mfma_f32_16x16x32_bf16 v[54:57], v[164:167], v[188:191], v[54:57]
	v_mfma_f32_16x16x32_bf16 v[46:49], v[156:159], v[196:199], v[46:49]
	v_mfma_f32_16x16x32_bf16 v[38:41], v[164:167], v[196:199], v[38:41]
	v_mfma_f32_16x16x32_bf16 v[30:33], v[156:159], v[212:215], v[30:33]
	v_mfma_f32_16x16x32_bf16 v[22:25], v[164:167], v[212:215], v[22:25]
	v_mfma_f32_16x16x32_bf16 v[14:17], v[156:159], v[220:223], v[14:17]
	v_mfma_f32_16x16x32_bf16 v[6:9], v[164:167], v[220:223], v[6:9]
	v_mfma_f32_16x16x32_bf16 v[62:65], v[160:163], v[192:195], v[62:65]
	v_mfma_f32_16x16x32_bf16 v[54:57], v[168:171], v[192:195], v[54:57]
	v_mfma_f32_16x16x32_bf16 v[46:49], v[160:163], v[208:211], v[46:49]
	v_mfma_f32_16x16x32_bf16 v[38:41], v[168:171], v[208:211], v[38:41]
	v_mfma_f32_16x16x32_bf16 v[30:33], v[160:163], v[216:219], v[30:33]
	v_mfma_f32_16x16x32_bf16 v[22:25], v[168:171], v[216:219], v[22:25]
	v_mfma_f32_16x16x32_bf16 v[14:17], v[160:163], v[224:227], v[14:17]
	v_mfma_f32_16x16x32_bf16 v[6:9], v[168:171], v[224:227], v[6:9]
	s_setprio 0
	s_setprio 1
	v_mfma_f32_16x16x32_bf16 v[58:61], v[172:175], v[188:191], v[58:61]
	v_mfma_f32_16x16x32_bf16 v[50:53], v[180:183], v[188:191], v[50:53]
	v_mfma_f32_16x16x32_bf16 v[42:45], v[172:175], v[196:199], v[42:45]
	v_mfma_f32_16x16x32_bf16 v[34:37], v[180:183], v[196:199], v[34:37]
	v_mfma_f32_16x16x32_bf16 v[26:29], v[172:175], v[212:215], v[26:29]
	v_mfma_f32_16x16x32_bf16 v[18:21], v[180:183], v[212:215], v[18:21]
	v_mfma_f32_16x16x32_bf16 v[10:13], v[172:175], v[220:223], v[10:13]
	v_mfma_f32_16x16x32_bf16 v[2:5], v[180:183], v[220:223], v[2:5]
	v_mfma_f32_16x16x32_bf16 v[58:61], v[176:179], v[192:195], v[58:61]
	v_mfma_f32_16x16x32_bf16 v[50:53], v[184:187], v[192:195], v[50:53]
	v_mfma_f32_16x16x32_bf16 v[42:45], v[176:179], v[208:211], v[42:45]
	v_mfma_f32_16x16x32_bf16 v[34:37], v[184:187], v[208:211], v[34:37]
	v_mfma_f32_16x16x32_bf16 v[26:29], v[176:179], v[216:219], v[26:29]
	v_mfma_f32_16x16x32_bf16 v[18:21], v[184:187], v[216:219], v[18:21]
	v_mfma_f32_16x16x32_bf16 v[10:13], v[176:179], v[224:227], v[10:13]
	v_mfma_f32_16x16x32_bf16 v[2:5], v[184:187], v[224:227], v[2:5]
	s_setprio 0
	s_barrier
	s_add_i32 s58, s58, 2
	s_add_u32 s6, s6, 0x100
	s_addc_u32 s7, s7, 0
	s_add_u32 s56, s56, 0x100
	s_addc_u32 s57, s57, 0
	s_cmp_gt_u32 s58, 13
	s_cbranch_scc0 .LBB0_667
	s_and_b64 vcc, exec, s[8:9]
	s_cbranch_vccz .LBB0_670
	s_barrier
